# norm loop: both rows' modulation chunks batched and issued before the row reduction; no wait between the x-row wait and the end of the item
# baseline (speedup 1.0000x reference)
; DI void ph_norm(const Params& p, int l, int bid, int nb) {
;     ...
;   for (int it = bid; it < ROWS / 8; it += nb) {
;     float4 v[2][4];
;     const float* mod[2];
; #pragma unroll
;     for (int rr = 0; rr < 2; ++rr) {
;       const int row = it * 8 + rr * 4 + w;
;       const int b = row / NTOK, t = row % NTOK;
;       const float* src = xsrc_row(p, l, b, t);
;       mod[rr] = MOD + ((size_t)l * 9 + (t < NCTX ? 8 : b)) * 3072;
; #pragma unroll
;       for (int i = 0; i < 4; ++i) v[rr][i] = *(const float4*)(src + (i * 64 + lane) * 4);
;     }
; #pragma unroll
;     for (int rr = 0; rr < 2; ++rr) {
;       const int row = it * 8 + rr * 4 + w;
;       float ss = 0.f;
; #pragma unroll
;       for (int i = 0; i < 4; ++i) ss += v[rr][i].x * v[rr][i].x + v[rr][i].y * v[rr][i].y + v[rr][i].z * v[rr][i].z + v[rr][i].w * v[rr][i].w;
;       ss = wave_sum(ss);
;       const float rstd = rsqrtf(ss * (1.f / DM) + EPS);
; #pragma unroll
;       for (int i = 0; i < 4; ++i) {
;         const int j = (i * 64 + lane) * 4;
;         const float4 gg = *(const float4*)(g + j);
;         const float4 sh = *(const float4*)(mod[rr] + j);
;         const float4 sc = *(const float4*)(mod[rr] + 1024 + j);
.LBB0_115:
	s_or_b64 exec, exec, s[8:9]
	v_lshlrev_b64 v[8:9], v16, v[8:9]
	v_lshl_add_u64 v[8:9], v[18:19], 0, v[8:9]
	v_lshlrev_b64 v[10:11], 12, v[10:11]
	v_lshl_add_u64 v[8:9], v[8:9], 0, v[10:11]
	v_lshl_add_u64 v[8:9], v[8:9], 0, v[46:47]
	global_load_dwordx4 v[28:31], v[8:9], off
	global_load_dwordx4 v[20:23], v[8:9], off offset:1024
	global_load_dwordx4 v[16:19], v[8:9], off offset:2048
	s_nop 0
	global_load_dwordx4 v[8:11], v[8:9], off offset:3072
	v_add_u32_e32 v45, s2, v58
	s_waitcnt vmcnt(0) lgkmcnt(0)
	v_mov_b32_e32 v70, v25
	v_mov_b32_e32 v71, v13
	v_mov_b32_e32 v58, v24
	v_mov_b32_e32 v59, v12
	v_mov_b32_e32 v78, v5
	v_mov_b32_e32 v79, v1
	v_mul_hi_i32_i24_e32 v85, 0x3000, v45
	v_mul_i32_i24_e32 v84, 0x3000, v45
	v_pk_mul_f32 v[70:71], v[70:71], v[70:71]
	v_mov_b32_e32 v72, v26
	v_mov_b32_e32 v73, v14
	v_mov_b32_e32 v76, v4
	v_mov_b32_e32 v77, v0
	v_pk_mul_f32 v[78:79], v[78:79], v[78:79]
	v_lshl_add_u64 v[84:85], s[0:1], 0, v[84:85]
	v_pk_fma_f32 v[58:59], v[58:59], v[58:59], v[70:71]
	s_mov_b64 s[12:13], 0x1000
	v_mov_b32_e32 v74, v27
	v_mov_b32_e32 v75, v15
	v_mov_b32_e32 v80, v6
	v_mov_b32_e32 v81, v2
	v_pk_fma_f32 v[70:71], v[76:77], v[76:77], v[78:79]
	v_pk_fma_f32 v[58:59], v[72:73], v[72:73], v[58:59]
	v_lshl_add_u64 v[78:79], v[84:85], 0, s[12:13]
	v_mov_b32_e32 v82, v7
	v_mov_b32_e32 v83, v3
	v_pk_fma_f32 v[70:71], v[80:81], v[80:81], v[70:71]
	v_lshl_add_u64 v[80:81], v[84:85], 0, v[46:47]
	v_pk_fma_f32 v[58:59], v[74:75], v[74:75], v[58:59]
	v_lshl_add_u64 v[74:75], v[78:79], 0, v[46:47]
	v_mov_b64_e32 v[66:67], v[104:105]
	v_mov_b64_e32 v[68:69], v[106:107]
	v_pk_fma_f32 v[82:83], v[82:83], v[82:83], v[70:71]
	global_load_dwordx4 v[70:73], v[80:81], off
	global_load_dwordx4 v[120:123], v[80:81], off offset:1024
	global_load_dwordx4 v[124:127], v[80:81], off offset:2048
	global_load_dwordx4 v[128:131], v[80:81], off offset:3072
	s_nop 0
	global_load_dwordx4 v[132:135], v[74:75], off offset:1024
	global_load_dwordx4 v[136:139], v[74:75], off offset:2048
	global_load_dwordx4 v[140:143], v[74:75], off offset:3072
	global_load_dwordx4 v[74:77], v[74:75], off
	v_add_u32_e32 v204, s2, v56
	v_mul_hi_i32_i24_e32 v207, 0x3000, v204
	v_mul_i32_i24_e32 v206, 0x3000, v204
	v_lshl_add_u64 v[206:207], s[0:1], 0, v[206:207]
	v_lshl_add_u64 v[208:209], v[206:207], 0, v[46:47]
	v_lshl_add_u64 v[206:207], v[206:207], 0, s[12:13]
	v_lshl_add_u64 v[206:207], v[206:207], 0, v[46:47]
	global_load_dwordx4 v[212:215], v[208:209], off
	global_load_dwordx4 v[156:159], v[208:209], off offset:1024
	global_load_dwordx4 v[196:199], v[208:209], off offset:2048
	global_load_dwordx4 v[200:203], v[208:209], off offset:3072
	global_load_dwordx4 v[216:219], v[206:207], off
	global_load_dwordx4 v[144:147], v[206:207], off offset:1024
	global_load_dwordx4 v[148:151], v[206:207], off offset:2048
	global_load_dwordx4 v[152:155], v[206:207], off offset:3072
	v_mov_b32_e32 v85, v58
	v_mov_b32_e32 v87, v82
	s_mov_b32 s8, 0x3a800000
	v_ashrrev_i32_e32 v45, 31, v44
	s_add_i32 s10, s10, s54
	s_mov_b32 s38, 0x800000
	s_cmpk_lt_i32 s10, 0x900
	v_mov_b32_e32 v94, v29
	v_mov_b32_e32 v95, v21
	v_mov_b32_e32 v92, v28
	v_mov_b32_e32 v93, v20
	v_mov_b32_e32 v102, v17
	v_mov_b32_e32 v103, v9
	v_pk_mul_f32 v[94:95], v[94:95], v[94:95]
	v_mov_b32_e32 v88, v30
	v_mov_b32_e32 v89, v22
	v_mov_b32_e32 v100, v16
	v_mov_b32_e32 v101, v8
	v_pk_mul_f32 v[102:103], v[102:103], v[102:103]
	v_pk_fma_f32 v[92:93], v[92:93], v[92:93], v[94:95]
	v_mov_b32_e32 v90, v31
	v_mov_b32_e32 v91, v23
	v_mov_b32_e32 v96, v18
	v_mov_b32_e32 v97, v10
	v_pk_fma_f32 v[94:95], v[100:101], v[100:101], v[102:103]
	v_pk_fma_f32 v[88:89], v[88:89], v[88:89], v[92:93]
	v_mov_b32_e32 v98, v19
	v_mov_b32_e32 v99, v11
	v_pk_fma_f32 v[92:93], v[96:97], v[96:97], v[94:95]
	v_pk_fma_f32 v[88:89], v[90:91], v[90:91], v[88:89]
	v_pk_fma_f32 v[90:91], v[98:99], v[98:99], v[92:93]
	v_mov_b32_e32 v84, v88
	v_mov_b32_e32 v58, v89
	v_mov_b32_e32 v86, v90
	v_pk_add_f32 v[58:59], v[84:85], v[58:59]
	v_mov_b32_e32 v82, v91
	v_pk_add_f32 v[58:59], v[58:59], v[86:87]
	v_lshl_add_u64 v[84:85], v[44:45], 0, v[36:37]
	v_pk_add_f32 v[58:59], v[58:59], v[82:83]
	ds_bpermute_b32 v83, v60, v59
	ds_bpermute_b32 v82, v60, v58
	v_lshlrev_b64 v[84:85], 6, v[84:85]
	v_lshl_add_u64 v[84:85], v[32:33], 0, v[84:85]
	s_waitcnt vmcnt(0) lgkmcnt(0)
	v_pk_add_f32 v[74:75], v[74:75], 1.0 op_sel_hi:[1,0]
	v_pk_add_f32 v[58:59], v[58:59], v[82:83]
	ds_bpermute_b32 v83, v61, v59
	ds_bpermute_b32 v82, v61, v58
	v_pk_add_f32 v[76:77], v[76:77], 1.0 op_sel_hi:[1,0]
	s_waitcnt lgkmcnt(0)
	v_pk_add_f32 v[58:59], v[58:59], v[82:83]
	ds_bpermute_b32 v83, v62, v59
	ds_bpermute_b32 v82, v62, v58
	s_waitcnt lgkmcnt(0)
	v_pk_add_f32 v[58:59], v[58:59], v[82:83]
	ds_bpermute_b32 v83, v63, v59
	ds_bpermute_b32 v82, v63, v58
	s_waitcnt lgkmcnt(0)
	v_pk_add_f32 v[58:59], v[58:59], v[82:83]
	ds_bpermute_b32 v83, v64, v59
	ds_bpermute_b32 v82, v64, v58
	s_waitcnt lgkmcnt(0)
	v_pk_add_f32 v[58:59], v[58:59], v[82:83]
	ds_bpermute_b32 v83, v65, v59
	ds_bpermute_b32 v82, v65, v58
	s_waitcnt lgkmcnt(0)
; DI size_t kblk(int row, int col, int nrows) { return ((size_t)(col >> 5) * nrows + row) * 32 + (col & 31); }
; DI unsigned pk2(float a, float b) { hwf32x2 f = {a, b}; hwbf16x2 r = __builtin_convertvector(f, hwbf16x2); return __builtin_bit_cast(unsigned, r); }
; DI void ph_norm(const Params& p, int l, int bid, int nb) {
;     ...
;       const float rstd = rsqrtf(ss * (1.f / DM) + EPS);
; #pragma unroll
;       for (int i = 0; i < 4; ++i) {
;         const int j = (i * 64 + lane) * 4;
;         const float4 gg = *(const float4*)(g + j);
;         const float4 sh = *(const float4*)(mod[rr] + j);
;         const float4 sc = *(const float4*)(mod[rr] + 1024 + j);
;         uint2 o;
;         o.x = pk2(v[rr][i].x * rstd * gg.x * (1.f + sc.x) + sh.x, v[rr][i].y * rstd * gg.y * (1.f + sc.y) + sh.y);
;         o.y = pk2(v[rr][i].z * rstd * gg.z * (1.f + sc.z) + sh.z, v[rr][i].w * rstd * gg.w * (1.f + sc.w) + sh.w);
;         *(uint2*)(H + kblk(row, j, ROWS)) = o;
;       }
	v_pk_add_f32 v[58:59], v[58:59], v[82:83]
	s_nop 0
	v_pk_fma_f32 v[58:59], v[58:59], s[8:9], v[162:163] op_sel_hi:[1,0,0]
	s_mov_b32 s8, 0x800000
	v_mul_f32_e32 v55, 0x4b800000, v59
	v_cmp_gt_f32_e32 vcc, s8, v59
	v_lshl_add_u64 v[82:83], v[78:79], 0, v[48:49]
	s_nop 0
	v_cndmask_b32_e32 v55, v59, v55, vcc
	v_rsq_f32_e32 v55, v55
	s_nop 0
	v_mul_f32_e32 v57, 0x45800000, v55
	v_cndmask_b32_e32 v86, v55, v57, vcc
	v_pk_mul_f32 v[24:25], v[24:25], v[86:87] op_sel_hi:[1,0]
	v_pk_mul_f32 v[26:27], v[26:27], v[86:87] op_sel_hi:[1,0]
	v_pk_mul_f32 v[24:25], v[66:67], v[24:25]
	v_pk_mul_f32 v[26:27], v[68:69], v[26:27]
	v_pk_fma_f32 v[24:25], v[74:75], v[24:25], v[70:71]
	v_pk_fma_f32 v[26:27], v[26:27], v[76:77], v[72:73]
	v_cvt_pk_bf16_f32 v24, v24, v25
	v_cvt_pk_bf16_f32 v25, v26, v27
	global_store_dwordx2 v[84:85], v[24:25], off
	v_mov_b64_e32 v[24:25], v[108:109]
	v_mov_b64_e32 v[26:27], v[110:111]
	s_nop 0
	v_mov_b64_e32 v[66:67], v[132:133]
	v_mov_b64_e32 v[68:69], v[134:135]
	v_mov_b64_e32 v[70:71], v[120:121]
	v_mov_b64_e32 v[72:73], v[122:123]
	v_pk_mul_f32 v[12:13], v[12:13], v[86:87] op_sel_hi:[1,0]
	v_pk_mul_f32 v[14:15], v[14:15], v[86:87] op_sel_hi:[1,0]
	v_lshl_add_u64 v[74:75], v[44:45], 0, v[38:39]
	v_lshlrev_b64 v[74:75], 6, v[74:75]
	v_lshl_add_u64 v[74:75], v[32:33], 0, v[74:75]
	v_lshl_add_u64 v[76:77], v[78:79], 0, v[50:51]
	v_pk_mul_f32 v[4:5], v[4:5], v[86:87] op_sel_hi:[1,0]
	v_pk_mul_f32 v[6:7], v[6:7], v[86:87] op_sel_hi:[1,0]
	v_pk_mul_f32 v[0:1], v[0:1], v[86:87] op_sel_hi:[1,0]
	v_pk_mul_f32 v[2:3], v[2:3], v[86:87] op_sel_hi:[1,0]
	v_add_u32_e32 v55, s2, v56
	v_mul_hi_i32_i24_e32 v57, 0x3000, v55
	v_mul_i32_i24_e32 v56, 0x3000, v55
	v_lshl_add_u64 v[56:57], s[0:1], 0, v[56:57]
	v_cmp_gt_f32_e32 vcc, s8, v58
	v_ashrrev_i32_e32 v55, 31, v54
	v_readlane_b32 s8, v254, 11
	v_pk_mul_f32 v[12:13], v[12:13], v[24:25]
	s_waitcnt lgkmcnt(0)
	v_pk_add_f32 v[24:25], v[66:67], 1.0 op_sel_hi:[1,0]
	v_pk_mul_f32 v[14:15], v[14:15], v[26:27]
	v_pk_add_f32 v[26:27], v[68:69], 1.0 op_sel_hi:[1,0]
	v_pk_fma_f32 v[12:13], v[12:13], v[24:25], v[70:71]
	v_pk_fma_f32 v[14:15], v[14:15], v[26:27], v[72:73]
	v_cvt_pk_bf16_f32 v12, v12, v13
	v_cvt_pk_bf16_f32 v13, v14, v15
	global_store_dwordx2 v[74:75], v[12:13], off
	v_mov_b64_e32 v[12:13], v[112:113]
	v_mov_b64_e32 v[14:15], v[114:115]
	s_nop 0
	v_mov_b64_e32 v[24:25], v[136:137]
	v_mov_b64_e32 v[26:27], v[138:139]
	v_mov_b64_e32 v[66:67], v[124:125]
	v_mov_b64_e32 v[68:69], v[126:127]
	v_lshl_add_u64 v[70:71], v[44:45], 0, v[40:41]
	v_lshlrev_b64 v[70:71], 6, v[70:71]
	v_lshl_add_u64 v[70:71], v[32:33], 0, v[70:71]
	v_lshl_add_u64 v[72:73], v[78:79], 0, v[52:53]
	v_pk_mul_f32 v[4:5], v[4:5], v[12:13]
	s_waitcnt lgkmcnt(0)
	v_pk_add_f32 v[12:13], v[24:25], 1.0 op_sel_hi:[1,0]
	v_pk_mul_f32 v[6:7], v[6:7], v[14:15]
	v_pk_add_f32 v[14:15], v[26:27], 1.0 op_sel_hi:[1,0]
	v_pk_fma_f32 v[4:5], v[4:5], v[12:13], v[66:67]
	v_pk_fma_f32 v[6:7], v[6:7], v[14:15], v[68:69]
	v_cvt_pk_bf16_f32 v4, v4, v5
	v_cvt_pk_bf16_f32 v5, v6, v7
	global_store_dwordx2 v[70:71], v[4:5], off
	v_mov_b64_e32 v[4:5], v[116:117]
	v_mov_b64_e32 v[6:7], v[118:119]
	s_nop 0
	v_mov_b64_e32 v[12:13], v[140:141]
	v_mov_b64_e32 v[14:15], v[142:143]
	v_mov_b64_e32 v[24:25], v[128:129]
	v_mov_b64_e32 v[26:27], v[130:131]
	v_lshl_add_u64 v[66:67], v[44:45], 0, v[42:43]
	v_lshlrev_b64 v[66:67], 6, v[66:67]
	v_lshl_add_u64 v[66:67], v[32:33], 0, v[66:67]
	v_lshl_add_u64 v[68:69], v[56:57], 0, s[12:13]
	v_lshl_add_u64 v[70:71], v[68:69], 0, v[46:47]
	v_mul_f32_e32 v45, 0x4b800000, v58
	v_cndmask_b32_e32 v45, v58, v45, vcc
	v_rsq_f32_e32 v45, v45
	v_add_u32_e32 v44, s8, v44
	v_mul_f32_e32 v58, 0x45800000, v45
	v_cndmask_b32_e32 v58, v45, v58, vcc
	v_pk_mul_f32 v[28:29], v[28:29], v[58:59] op_sel_hi:[1,0]
	v_pk_mul_f32 v[30:31], v[30:31], v[58:59] op_sel_hi:[1,0]
	v_pk_mul_f32 v[20:21], v[20:21], v[58:59] op_sel_hi:[1,0]
	v_pk_mul_f32 v[22:23], v[22:23], v[58:59] op_sel_hi:[1,0]
	v_pk_mul_f32 v[16:17], v[16:17], v[58:59] op_sel_hi:[1,0]
	v_pk_mul_f32 v[18:19], v[18:19], v[58:59] op_sel_hi:[1,0]
	v_pk_mul_f32 v[8:9], v[8:9], v[58:59] op_sel_hi:[1,0]
	v_pk_mul_f32 v[10:11], v[10:11], v[58:59] op_sel_hi:[1,0]
	v_pk_mul_f32 v[0:1], v[0:1], v[4:5]
	s_waitcnt lgkmcnt(0)
; DI size_t kblk(int row, int col, int nrows) { return ((size_t)(col >> 5) * nrows + row) * 32 + (col & 31); }
; DI unsigned pk2(float a, float b) { hwf32x2 f = {a, b}; hwbf16x2 r = __builtin_convertvector(f, hwbf16x2); return __builtin_bit_cast(unsigned, r); }
; DI void ph_norm(const Params& p, int l, int bid, int nb) {
;     ...
;       for (int i = 0; i < 4; ++i) {
;         const int j = (i * 64 + lane) * 4;
;         const float4 gg = *(const float4*)(g + j);
;         const float4 sh = *(const float4*)(mod[rr] + j);
;         const float4 sc = *(const float4*)(mod[rr] + 1024 + j);
;         uint2 o;
;         o.x = pk2(v[rr][i].x * rstd * gg.x * (1.f + sc.x) + sh.x, v[rr][i].y * rstd * gg.y * (1.f + sc.y) + sh.y);
;         o.y = pk2(v[rr][i].z * rstd * gg.z * (1.f + sc.z) + sh.z, v[rr][i].w * rstd * gg.w * (1.f + sc.w) + sh.w);
;         *(uint2*)(H + kblk(row, j, ROWS)) = o;
;       }
	v_pk_add_f32 v[4:5], v[12:13], 1.0 op_sel_hi:[1,0]
	v_pk_mul_f32 v[2:3], v[2:3], v[6:7]
	v_pk_add_f32 v[6:7], v[14:15], 1.0 op_sel_hi:[1,0]
	v_pk_fma_f32 v[0:1], v[0:1], v[4:5], v[24:25]
	v_pk_fma_f32 v[2:3], v[2:3], v[6:7], v[26:27]
	v_cvt_pk_bf16_f32 v0, v0, v1
	v_cvt_pk_bf16_f32 v1, v2, v3
	global_store_dwordx2 v[66:67], v[0:1], off
	v_mov_b64_e32 v[0:1], v[104:105]
	v_mov_b64_e32 v[2:3], v[106:107]
	s_nop 0
	v_mov_b64_e32 v[4:5], v[216:217]
	v_mov_b64_e32 v[6:7], v[218:219]
	v_lshl_add_u64 v[24:25], v[56:57], 0, v[46:47]
	v_mov_b64_e32 v[12:13], v[212:213]
	v_mov_b64_e32 v[14:15], v[214:215]
	v_lshl_add_u64 v[26:27], v[54:55], 0, v[36:37]
	v_lshlrev_b64 v[26:27], 6, v[26:27]
	v_lshl_add_u64 v[26:27], v[32:33], 0, v[26:27]
	v_lshl_add_u64 v[56:57], v[68:69], 0, v[48:49]
	v_pk_mul_f32 v[0:1], v[0:1], v[28:29]
	s_waitcnt lgkmcnt(0)
	v_pk_add_f32 v[4:5], v[4:5], 1.0 op_sel_hi:[1,0]
	v_pk_mul_f32 v[2:3], v[2:3], v[30:31]
	v_pk_add_f32 v[6:7], v[6:7], 1.0 op_sel_hi:[1,0]
	v_pk_fma_f32 v[0:1], v[4:5], v[0:1], v[12:13]
	v_pk_fma_f32 v[2:3], v[2:3], v[6:7], v[14:15]
	v_cvt_pk_bf16_f32 v0, v0, v1
	v_cvt_pk_bf16_f32 v1, v2, v3
	global_store_dwordx2 v[26:27], v[0:1], off
	v_mov_b64_e32 v[0:1], v[108:109]
	v_mov_b64_e32 v[2:3], v[110:111]
	s_nop 0
	v_mov_b64_e32 v[4:5], v[144:145]
	v_mov_b64_e32 v[6:7], v[146:147]
	v_mov_b64_e32 v[12:13], v[156:157]
	v_mov_b64_e32 v[14:15], v[158:159]
	v_lshl_add_u64 v[26:27], v[54:55], 0, v[38:39]
	v_lshlrev_b64 v[26:27], 6, v[26:27]
	v_lshl_add_u64 v[26:27], v[32:33], 0, v[26:27]
	v_lshl_add_u64 v[28:29], v[68:69], 0, v[50:51]
	v_pk_mul_f32 v[0:1], v[20:21], v[0:1]
	s_waitcnt lgkmcnt(0)
	v_pk_add_f32 v[4:5], v[4:5], 1.0 op_sel_hi:[1,0]
	v_pk_mul_f32 v[2:3], v[22:23], v[2:3]
	v_pk_add_f32 v[6:7], v[6:7], 1.0 op_sel_hi:[1,0]
	v_pk_fma_f32 v[0:1], v[0:1], v[4:5], v[12:13]
	v_pk_fma_f32 v[2:3], v[2:3], v[6:7], v[14:15]
	v_cvt_pk_bf16_f32 v0, v0, v1
	v_cvt_pk_bf16_f32 v1, v2, v3
	global_store_dwordx2 v[26:27], v[0:1], off
	v_mov_b64_e32 v[0:1], v[112:113]
	v_mov_b64_e32 v[2:3], v[114:115]
	s_nop 0
	v_mov_b64_e32 v[4:5], v[148:149]
	v_mov_b64_e32 v[6:7], v[150:151]
	v_mov_b64_e32 v[12:13], v[196:197]
	v_mov_b64_e32 v[14:15], v[198:199]
	v_lshl_add_u64 v[20:21], v[54:55], 0, v[40:41]
	v_lshlrev_b64 v[20:21], 6, v[20:21]
	v_lshl_add_u64 v[20:21], v[32:33], 0, v[20:21]
	v_lshl_add_u64 v[22:23], v[68:69], 0, v[52:53]
	v_pk_mul_f32 v[0:1], v[16:17], v[0:1]
	s_waitcnt lgkmcnt(0)
	v_pk_add_f32 v[4:5], v[4:5], 1.0 op_sel_hi:[1,0]
	v_pk_mul_f32 v[2:3], v[18:19], v[2:3]
	v_pk_add_f32 v[6:7], v[6:7], 1.0 op_sel_hi:[1,0]
	v_pk_fma_f32 v[0:1], v[0:1], v[4:5], v[12:13]
	v_pk_fma_f32 v[2:3], v[2:3], v[6:7], v[14:15]
	v_cvt_pk_bf16_f32 v0, v0, v1
	v_cvt_pk_bf16_f32 v1, v2, v3
	global_store_dwordx2 v[20:21], v[0:1], off
	v_mov_b64_e32 v[0:1], v[116:117]
	v_mov_b64_e32 v[2:3], v[118:119]
	s_nop 0
	v_mov_b64_e32 v[4:5], v[152:153]
	v_mov_b64_e32 v[6:7], v[154:155]
	v_mov_b64_e32 v[12:13], v[200:201]
	v_mov_b64_e32 v[14:15], v[202:203]
	v_lshl_add_u64 v[16:17], v[54:55], 0, v[42:43]
	v_lshlrev_b64 v[16:17], 6, v[16:17]
	v_lshl_add_u64 v[16:17], v[32:33], 0, v[16:17]
	v_pk_mul_f32 v[0:1], v[8:9], v[0:1]
	s_waitcnt lgkmcnt(0)
	v_pk_add_f32 v[4:5], v[4:5], 1.0 op_sel_hi:[1,0]
	v_pk_mul_f32 v[2:3], v[10:11], v[2:3]
	v_pk_add_f32 v[6:7], v[6:7], 1.0 op_sel_hi:[1,0]
	v_pk_fma_f32 v[0:1], v[0:1], v[4:5], v[12:13]
	v_pk_fma_f32 v[2:3], v[2:3], v[6:7], v[14:15]
	v_cvt_pk_bf16_f32 v0, v0, v1
	v_cvt_pk_bf16_f32 v1, v2, v3
	global_store_dwordx2 v[16:17], v[0:1], off
	s_cbranch_scc0 .LBB0_124
